# grid barrier: XCC leaders wait on the cross-XCC arrival counter (TOP >= target) instead of the release generation word (one hop less) on v28
# speedup vs baseline: 1.0023x; 1.0007x over previous
.LBB0_151:
	s_or_b64 exec, exec, s[14:15]
	v_cvt_f32_u32_e32 v3, v0
	s_waitcnt vmcnt(0)
	v_readfirstlane_b32 s3, v2
	buffer_inv sc1
	s_add_u32 s14, s8, 0xe003400
	s_addc_u32 s15, s9, 0
	v_rcp_iflag_f32_e32 v3, v3
	v_add_u32_e32 v1, s3, v1
	v_add_u32_e32 v4, 1, v1
	s_mov_b64 s[16:17], -1
	v_mul_f32_e32 v2, 0x4f7ffffe, v3
	v_cvt_u32_f32_e32 v2, v2
	v_sub_u32_e32 v3, 0, v0
	v_mul_lo_u32 v3, v3, v2
	v_mul_hi_u32 v3, v2, v3
	v_add_u32_e32 v2, v2, v3
	v_mul_hi_u32 v2, v1, v2
	v_mul_lo_u32 v3, v2, v0
	v_sub_u32_e32 v1, v1, v3
	v_add_u32_e32 v5, 1, v2
	v_cmp_ge_u32_e32 vcc, v1, v0
	v_sub_u32_e32 v3, v1, v0
	s_nop 0
	v_cndmask_b32_e32 v2, v2, v5, vcc
	v_cndmask_b32_e32 v1, v1, v3, vcc
	v_add_u32_e32 v3, 1, v2
	v_cmp_ge_u32_e32 vcc, v1, v0
	s_nop 1
	v_cndmask_b32_e32 v2, v2, v3, vcc
	v_mul_lo_u32 v1, v0, v2
	v_add_u32_e32 v0, v1, v0
	v_mov_b32_e32 v5, v0
	v_cmp_ne_u32_e32 vcc, v4, v0
	v_mov_b32_e32 v0, 0x100
	v_mov_b32_e32 v1, 0
	v_lshl_add_u64 v[0:1], s[14:15], 0, v[0:1]
	s_and_saveexec_b64 s[12:13], vcc
	s_cbranch_execz .LBB0_163
	v_mov_b32_e32 v0, 0
	global_load_dword v1, v0, s[14:15] sc1
	s_mov_b64 s[20:21], 0
	s_waitcnt vmcnt(0)
	v_cmp_lt_u32_e32 vcc, v1, v5
	s_and_saveexec_b64 s[18:19], vcc
	s_cbranch_execz .LBB0_162
	s_add_u32 s16, s8, 0xe000200
	s_addc_u32 s17, s9, 0
	s_mov_b32 s3, 1
	s_mov_b64 s[8:9], 0
	s_branch .LBB0_155

.LBB0_159:
	global_load_dword v1, v0, s[14:15] sc1
	s_add_i32 s3, s3, 1
	s_mov_b64 s[22:23], -1
	s_waitcnt vmcnt(0)
	v_cmp_ge_u32_e32 vcc, v1, v5
	s_orn2_b64 s[34:35], vcc, exec
	s_branch .LBB0_154

.LBB0_454:
	s_or_b64 exec, exec, s[16:17]
	v_cvt_f32_u32_e32 v3, v0
	s_waitcnt vmcnt(0)
	v_readfirstlane_b32 s14, v2
	buffer_inv sc1
	s_add_u32 s16, s10, 0xe003400
	s_addc_u32 s17, s11, 0
	v_rcp_iflag_f32_e32 v3, v3
	v_add_u32_e32 v1, s14, v1
	v_add_u32_e32 v4, 1, v1
	s_mov_b64 s[18:19], -1
	v_mul_f32_e32 v2, 0x4f7ffffe, v3
	v_cvt_u32_f32_e32 v2, v2
	v_sub_u32_e32 v3, 0, v0
	v_mul_lo_u32 v3, v3, v2
	v_mul_hi_u32 v3, v2, v3
	v_add_u32_e32 v2, v2, v3
	v_mul_hi_u32 v2, v1, v2
	v_mul_lo_u32 v3, v2, v0
	v_sub_u32_e32 v1, v1, v3
	v_add_u32_e32 v5, 1, v2
	v_cmp_ge_u32_e32 vcc, v1, v0
	v_sub_u32_e32 v3, v1, v0
	s_nop 0
	v_cndmask_b32_e32 v2, v2, v5, vcc
	v_cndmask_b32_e32 v1, v1, v3, vcc
	v_add_u32_e32 v3, 1, v2
	v_cmp_ge_u32_e32 vcc, v1, v0
	s_nop 1
	v_cndmask_b32_e32 v2, v2, v3, vcc
	v_mul_lo_u32 v1, v0, v2
	v_add_u32_e32 v0, v1, v0
	v_mov_b32_e32 v5, v0
	v_cmp_ne_u32_e32 vcc, v4, v0
	v_mov_b32_e32 v0, 0x100
	v_mov_b32_e32 v1, 0
	v_lshl_add_u64 v[0:1], s[16:17], 0, v[0:1]
	s_and_saveexec_b64 s[14:15], vcc
	s_cbranch_execz .LBB0_466
	v_mov_b32_e32 v0, 0
	global_load_dword v1, v0, s[16:17] sc1
	s_mov_b64 s[34:35], 0
	s_waitcnt vmcnt(0)
	v_cmp_lt_u32_e32 vcc, v1, v5
	s_and_saveexec_b64 s[22:23], vcc
	s_cbranch_execz .LBB0_465
	s_add_u32 s18, s10, 0xe000200
	s_addc_u32 s19, s11, 0
	s_mov_b32 s26, 1
	s_mov_b64 s[10:11], 0
	s_branch .LBB0_458

.LBB0_462:
	global_load_dword v1, v0, s[16:17] sc1
	s_add_i32 s26, s26, 1
	s_mov_b64 s[36:37], -1
	s_waitcnt vmcnt(0)
	v_cmp_ge_u32_e32 vcc, v1, v5
	s_orn2_b64 s[40:41], vcc, exec
	s_branch .LBB0_457

.LBB0_609:
	s_or_b64 exec, exec, s[16:17]
	v_cvt_f32_u32_e32 v3, v0
	s_waitcnt vmcnt(0)
	v_readfirstlane_b32 s14, v2
	buffer_inv sc1
	s_add_u32 s16, s10, 0xe003400
	s_addc_u32 s17, s11, 0
	v_rcp_iflag_f32_e32 v3, v3
	v_add_u32_e32 v1, s14, v1
	v_add_u32_e32 v4, 1, v1
	s_mov_b64 s[18:19], -1
	v_mul_f32_e32 v2, 0x4f7ffffe, v3
	v_cvt_u32_f32_e32 v2, v2
	v_sub_u32_e32 v3, 0, v0
	v_mul_lo_u32 v3, v3, v2
	v_mul_hi_u32 v3, v2, v3
	v_add_u32_e32 v2, v2, v3
	v_mul_hi_u32 v2, v1, v2
	v_mul_lo_u32 v3, v2, v0
	v_sub_u32_e32 v1, v1, v3
	v_add_u32_e32 v5, 1, v2
	v_cmp_ge_u32_e32 vcc, v1, v0
	v_sub_u32_e32 v3, v1, v0
	s_nop 0
	v_cndmask_b32_e32 v2, v2, v5, vcc
	v_cndmask_b32_e32 v1, v1, v3, vcc
	v_add_u32_e32 v3, 1, v2
	v_cmp_ge_u32_e32 vcc, v1, v0
	s_nop 1
	v_cndmask_b32_e32 v2, v2, v3, vcc
	v_mul_lo_u32 v1, v0, v2
	v_add_u32_e32 v0, v1, v0
	v_mov_b32_e32 v5, v0
	v_cmp_ne_u32_e32 vcc, v4, v0
	v_mov_b32_e32 v0, 0x100
	v_mov_b32_e32 v1, 0
	v_lshl_add_u64 v[0:1], s[16:17], 0, v[0:1]
	s_and_saveexec_b64 s[14:15], vcc
	s_cbranch_execz .LBB0_621
	v_mov_b32_e32 v0, 0
	global_load_dword v1, v0, s[16:17] sc1
	s_mov_b64 s[36:37], 0
	s_waitcnt vmcnt(0)
	v_cmp_lt_u32_e32 vcc, v1, v5
	s_and_saveexec_b64 s[34:35], vcc
	s_cbranch_execz .LBB0_620
	s_add_u32 s18, s10, 0xe000200
	s_addc_u32 s19, s11, 0
	s_mov_b32 s26, 1
	s_mov_b64 s[10:11], 0
	s_branch .LBB0_613

.LBB0_617:
	global_load_dword v1, v0, s[16:17] sc1
	s_add_i32 s26, s26, 1
	s_mov_b64 s[38:39], -1
	s_waitcnt vmcnt(0)
	v_cmp_ge_u32_e32 vcc, v1, v5
	s_orn2_b64 s[42:43], vcc, exec
	s_branch .LBB0_612

.LBB0_1023:
	s_or_b64 exec, exec, s[18:19]
	v_cvt_f32_u32_e32 v3, v0
	s_waitcnt vmcnt(0)
	v_readfirstlane_b32 s16, v2
	buffer_inv sc1
	s_add_u32 s18, s12, 0xe003400
	s_addc_u32 s19, s13, 0
	v_rcp_iflag_f32_e32 v3, v3
	v_add_u32_e32 v1, s16, v1
	v_add_u32_e32 v4, 1, v1
	s_mov_b64 s[36:37], -1
	v_mul_f32_e32 v2, 0x4f7ffffe, v3
	v_cvt_u32_f32_e32 v2, v2
	v_sub_u32_e32 v3, 0, v0
	v_mul_lo_u32 v3, v3, v2
	v_mul_hi_u32 v3, v2, v3
	v_add_u32_e32 v2, v2, v3
	v_mul_hi_u32 v2, v1, v2
	v_mul_lo_u32 v3, v2, v0
	v_sub_u32_e32 v1, v1, v3
	v_add_u32_e32 v5, 1, v2
	v_cmp_ge_u32_e32 vcc, v1, v0
	v_sub_u32_e32 v3, v1, v0
	s_nop 0
	v_cndmask_b32_e32 v2, v2, v5, vcc
	v_cndmask_b32_e32 v1, v1, v3, vcc
	v_add_u32_e32 v3, 1, v2
	v_cmp_ge_u32_e32 vcc, v1, v0
	s_nop 1
	v_cndmask_b32_e32 v2, v2, v3, vcc
	v_mul_lo_u32 v1, v0, v2
	v_add_u32_e32 v0, v1, v0
	v_mov_b32_e32 v5, v0
	v_cmp_ne_u32_e32 vcc, v4, v0
	v_mov_b32_e32 v0, 0x100
	v_mov_b32_e32 v1, 0
	v_lshl_add_u64 v[0:1], s[18:19], 0, v[0:1]
	s_and_saveexec_b64 s[16:17], vcc
	s_cbranch_execz .LBB0_1035
	v_mov_b32_e32 v0, 0
	global_load_dword v1, v0, s[18:19] sc1
	s_mov_b64 s[40:41], 0
	s_waitcnt vmcnt(0)
	v_cmp_lt_u32_e32 vcc, v1, v5
	s_and_saveexec_b64 s[38:39], vcc
	s_cbranch_execz .LBB0_1034
	s_add_u32 s36, s12, 0xe000200
	s_addc_u32 s37, s13, 0
	s_mov_b32 s26, 1
	s_mov_b64 s[12:13], 0
	s_branch .LBB0_1027

.LBB0_1031:
	global_load_dword v1, v0, s[18:19] sc1
	s_add_i32 s26, s26, 1
	s_mov_b64 s[42:43], -1
	s_waitcnt vmcnt(0)
	v_cmp_ge_u32_e32 vcc, v1, v5
	s_orn2_b64 s[46:47], vcc, exec
	s_branch .LBB0_1026

.LBB0_1324:
	s_or_b64 exec, exec, s[18:19]
	v_cvt_f32_u32_e32 v3, v0
	s_waitcnt vmcnt(0)
	v_readfirstlane_b32 s16, v2
	buffer_inv sc1
	s_add_u32 s18, s12, 0xe003400
	s_addc_u32 s19, s13, 0
	v_rcp_iflag_f32_e32 v3, v3
	v_add_u32_e32 v1, s16, v1
	v_add_u32_e32 v4, 1, v1
	s_mov_b64 s[20:21], -1
	v_mul_f32_e32 v2, 0x4f7ffffe, v3
	v_cvt_u32_f32_e32 v2, v2
	v_sub_u32_e32 v3, 0, v0
	v_mul_lo_u32 v3, v3, v2
	v_mul_hi_u32 v3, v2, v3
	v_add_u32_e32 v2, v2, v3
	v_mul_hi_u32 v2, v1, v2
	v_mul_lo_u32 v3, v2, v0
	v_sub_u32_e32 v1, v1, v3
	v_add_u32_e32 v5, 1, v2
	v_cmp_ge_u32_e32 vcc, v1, v0
	v_sub_u32_e32 v3, v1, v0
	s_nop 0
	v_cndmask_b32_e32 v2, v2, v5, vcc
	v_cndmask_b32_e32 v1, v1, v3, vcc
	v_add_u32_e32 v3, 1, v2
	v_cmp_ge_u32_e32 vcc, v1, v0
	s_nop 1
	v_cndmask_b32_e32 v2, v2, v3, vcc
	v_mul_lo_u32 v1, v0, v2
	v_add_u32_e32 v0, v1, v0
	v_mov_b32_e32 v5, v0
	v_cmp_ne_u32_e32 vcc, v4, v0
	v_mov_b32_e32 v0, 0x100
	v_mov_b32_e32 v1, 0
	v_lshl_add_u64 v[0:1], s[18:19], 0, v[0:1]
	s_and_saveexec_b64 s[16:17], vcc
	s_cbranch_execz .LBB0_1336
	v_mov_b32_e32 v0, 0
	global_load_dword v1, v0, s[18:19] sc1
	s_mov_b64 s[38:39], 0
	s_waitcnt vmcnt(0)
	v_cmp_lt_u32_e32 vcc, v1, v5
	s_and_saveexec_b64 s[36:37], vcc
	s_cbranch_execz .LBB0_1335
	s_add_u32 s20, s12, 0xe000200
	s_addc_u32 s21, s13, 0
	s_mov_b32 s26, 1
	s_mov_b64 s[12:13], 0
	s_branch .LBB0_1328

.LBB0_1332:
	global_load_dword v1, v0, s[18:19] sc1
	s_add_i32 s26, s26, 1
	s_mov_b64 s[40:41], -1
	s_waitcnt vmcnt(0)
	v_cmp_ge_u32_e32 vcc, v1, v5
	s_orn2_b64 s[44:45], vcc, exec
	s_branch .LBB0_1327

.LBB0_1479:
	s_or_b64 exec, exec, s[18:19]
	v_cvt_f32_u32_e32 v3, v0
	s_waitcnt vmcnt(0)
	v_readfirstlane_b32 s16, v2
	buffer_inv sc1
	s_add_u32 s18, s12, 0xe003400
	s_addc_u32 s19, s13, 0
	v_rcp_iflag_f32_e32 v3, v3
	v_add_u32_e32 v1, s16, v1
	v_add_u32_e32 v4, 1, v1
	s_mov_b64 s[20:21], -1
	v_mul_f32_e32 v2, 0x4f7ffffe, v3
	v_cvt_u32_f32_e32 v2, v2
	v_sub_u32_e32 v3, 0, v0
	v_mul_lo_u32 v3, v3, v2
	v_mul_hi_u32 v3, v2, v3
	v_add_u32_e32 v2, v2, v3
	v_mul_hi_u32 v2, v1, v2
	v_mul_lo_u32 v3, v2, v0
	v_sub_u32_e32 v1, v1, v3
	v_add_u32_e32 v5, 1, v2
	v_cmp_ge_u32_e32 vcc, v1, v0
	v_sub_u32_e32 v3, v1, v0
	s_nop 0
	v_cndmask_b32_e32 v2, v2, v5, vcc
	v_cndmask_b32_e32 v1, v1, v3, vcc
	v_add_u32_e32 v3, 1, v2
	v_cmp_ge_u32_e32 vcc, v1, v0
	s_nop 1
	v_cndmask_b32_e32 v2, v2, v3, vcc
	v_mul_lo_u32 v1, v0, v2
	v_add_u32_e32 v0, v1, v0
	v_mov_b32_e32 v5, v0
	v_cmp_ne_u32_e32 vcc, v4, v0
	v_mov_b32_e32 v0, 0x100
	v_mov_b32_e32 v1, 0
	v_lshl_add_u64 v[0:1], s[18:19], 0, v[0:1]
	s_and_saveexec_b64 s[16:17], vcc
	s_cbranch_execz .LBB0_1491
	v_mov_b32_e32 v0, 0
	global_load_dword v1, v0, s[18:19] sc1
	s_mov_b64 s[36:37], 0
	s_waitcnt vmcnt(0)
	v_cmp_lt_u32_e32 vcc, v1, v5
	s_and_saveexec_b64 s[22:23], vcc
	s_cbranch_execz .LBB0_1490
	s_add_u32 s20, s12, 0xe000200
	s_addc_u32 s21, s13, 0
	s_mov_b32 s26, 1
	s_mov_b64 s[12:13], 0
	s_branch .LBB0_1483

.LBB0_1487:
	global_load_dword v1, v0, s[18:19] sc1
	s_add_i32 s26, s26, 1
	s_mov_b64 s[38:39], -1
	s_waitcnt vmcnt(0)
	v_cmp_ge_u32_e32 vcc, v1, v5
	s_orn2_b64 s[42:43], vcc, exec
	s_branch .LBB0_1482

.LBB0_1797:
	s_or_b64 exec, exec, s[18:19]
	v_cvt_f32_u32_e32 v3, v0
	s_waitcnt vmcnt(0)
	v_readfirstlane_b32 s16, v2
	buffer_inv sc1
	s_add_u32 s18, s10, 0xe003400
	s_addc_u32 s19, s11, 0
	v_rcp_iflag_f32_e32 v3, v3
	v_add_u32_e32 v1, s16, v1
	v_add_u32_e32 v4, 1, v1
	s_mov_b64 s[20:21], -1
	v_mul_f32_e32 v2, 0x4f7ffffe, v3
	v_cvt_u32_f32_e32 v2, v2
	v_sub_u32_e32 v3, 0, v0
	v_mul_lo_u32 v3, v3, v2
	v_mul_hi_u32 v3, v2, v3
	v_add_u32_e32 v2, v2, v3
	v_mul_hi_u32 v2, v1, v2
	v_mul_lo_u32 v3, v2, v0
	v_sub_u32_e32 v1, v1, v3
	v_add_u32_e32 v5, 1, v2
	v_cmp_ge_u32_e32 vcc, v1, v0
	v_sub_u32_e32 v3, v1, v0
	s_nop 0
	v_cndmask_b32_e32 v2, v2, v5, vcc
	v_cndmask_b32_e32 v1, v1, v3, vcc
	v_add_u32_e32 v3, 1, v2
	v_cmp_ge_u32_e32 vcc, v1, v0
	s_nop 1
	v_cndmask_b32_e32 v2, v2, v3, vcc
	v_mul_lo_u32 v1, v0, v2
	v_add_u32_e32 v0, v1, v0
	v_mov_b32_e32 v5, v0
	v_cmp_ne_u32_e32 vcc, v4, v0
	v_mov_b32_e32 v0, 0x100
	v_mov_b32_e32 v1, 0
	v_lshl_add_u64 v[0:1], s[18:19], 0, v[0:1]
	s_and_saveexec_b64 s[16:17], vcc
	s_cbranch_execz .LBB0_1809
	v_mov_b32_e32 v0, 0
	global_load_dword v1, v0, s[18:19] sc1
	s_mov_b64 s[34:35], 0
	s_waitcnt vmcnt(0)
	v_cmp_lt_u32_e32 vcc, v1, v5
	s_and_saveexec_b64 s[22:23], vcc
	s_cbranch_execz .LBB0_1808
	s_add_u32 s20, s10, 0xe000200
	s_addc_u32 s21, s11, 0
	s_mov_b32 s26, 1
	s_mov_b64 s[10:11], 0
	s_branch .LBB0_1801

.LBB0_1805:
	global_load_dword v1, v0, s[18:19] sc1
	s_add_i32 s26, s26, 1
	s_mov_b64 s[36:37], -1
	s_waitcnt vmcnt(0)
	v_cmp_ge_u32_e32 vcc, v1, v5
	s_orn2_b64 s[40:41], vcc, exec
	s_branch .LBB0_1800

.LBB0_1893:
	s_or_b64 exec, exec, s[20:21]
	v_cvt_f32_u32_e32 v3, v0
	s_waitcnt vmcnt(0)
	v_readfirstlane_b32 s18, v2
	buffer_inv sc1
	s_add_u32 s20, s4, 0xe003400
	s_addc_u32 s21, s5, 0
	v_rcp_iflag_f32_e32 v3, v3
	v_add_u32_e32 v1, s18, v1
	v_add_u32_e32 v4, 1, v1
	s_mov_b64 s[22:23], -1
	v_mul_f32_e32 v2, 0x4f7ffffe, v3
	v_cvt_u32_f32_e32 v2, v2
	v_sub_u32_e32 v3, 0, v0
	v_mul_lo_u32 v3, v3, v2
	v_mul_hi_u32 v3, v2, v3
	v_add_u32_e32 v2, v2, v3
	v_mul_hi_u32 v2, v1, v2
	v_mul_lo_u32 v3, v2, v0
	v_sub_u32_e32 v1, v1, v3
	v_add_u32_e32 v5, 1, v2
	v_cmp_ge_u32_e32 vcc, v1, v0
	v_sub_u32_e32 v3, v1, v0
	s_nop 0
	v_cndmask_b32_e32 v2, v2, v5, vcc
	v_cndmask_b32_e32 v1, v1, v3, vcc
	v_add_u32_e32 v3, 1, v2
	v_cmp_ge_u32_e32 vcc, v1, v0
	s_nop 1
	v_cndmask_b32_e32 v2, v2, v3, vcc
	v_mul_lo_u32 v1, v0, v2
	v_add_u32_e32 v0, v1, v0
	v_mov_b32_e32 v5, v0
	v_cmp_ne_u32_e32 vcc, v4, v0
	v_mov_b32_e32 v0, 0x100
	v_mov_b32_e32 v1, 0
	v_lshl_add_u64 v[0:1], s[20:21], 0, v[0:1]
	s_and_saveexec_b64 s[18:19], vcc
	s_cbranch_execz .LBB0_1905
	v_mov_b32_e32 v0, 0
	global_load_dword v1, v0, s[20:21] sc1
	s_mov_b64 s[36:37], 0
	s_waitcnt vmcnt(0)
	v_cmp_lt_u32_e32 vcc, v1, v5
	s_and_saveexec_b64 s[34:35], vcc
	s_cbranch_execz .LBB0_1904
	s_add_u32 s22, s4, 0xe000200
	s_addc_u32 s23, s5, 0
	s_mov_b32 s25, 1
	s_mov_b64 s[4:5], 0
	s_branch .LBB0_1897

.LBB0_1901:
	global_load_dword v1, v0, s[20:21] sc1
	s_add_i32 s25, s25, 1
	s_mov_b64 s[38:39], -1
	s_waitcnt vmcnt(0)
	v_cmp_ge_u32_e32 vcc, v1, v5
	s_orn2_b64 s[42:43], vcc, exec
	s_branch .LBB0_1896
